# final rmsnorm output written with non-temporal (streaming) full-row stores: the output is never re-read on chip
# speedup vs baseline: 1.0061x; 1.0061x over previous
; DI void rmsnorm_phase(const float* __restrict__ X, const float* __restrict__ g, bf16_t* __restrict__ H, float* __restrict__ OF) {
;     ...
;   for (int row = gw; row < T; row += nw) {
;     const float* xr = X + (size_t)row * D;
;     f32x4 v[8];
;     float ss = 0.f;
; #pragma unroll
;     for (int i = 0; i < 8; ++i) { v[i] = *(const f32x4*)(xr + lane * 4 + 256 * i); ss += v[i][0] * v[i][0] + v[i][1] * v[i][1] + v[i][2] * v[i][2] + v[i][3] * v[i][3]; }
;     ss = wave_sum(ss);
;     const float rstd = rsqrtf(ss * (1.f / D) + EPS);
; #pragma unroll
;     for (int i = 0; i < 8; ++i) {
;       const f32x4 gg = *(const f32x4*)(g + lane * 4 + 256 * i);
;       f32x4 o = v[i] * rstd * gg;
;       if (H) { u32x2 w; w.x = pk_bf16(o[0], o[1]); w.y = pk_bf16(o[2], o[3]); *(u32x2*)(H + (size_t)row * D + lane * 4 + 256 * i) = w; }
;       else *(f32x4*)(OF + (size_t)row * D + lane * 4 + 256 * i) = o;
;     }
;   }
.LBB0_1709:
	global_load_dwordx4 v[42:45], v[34:35], off offset:-4096
	global_load_dwordx4 v[46:49], v[34:35], off offset:-3072
	global_load_dwordx4 v[50:53], v[34:35], off offset:-2048
	global_load_dwordx4 v[54:57], v[34:35], off offset:-1024
	global_load_dwordx4 v[58:61], v[34:35], off
	global_load_dwordx4 v[62:65], v[34:35], off offset:1024
	global_load_dwordx4 v[66:69], v[34:35], off offset:2048
	global_load_dwordx4 v[70:73], v[34:35], off offset:3072
	v_add_u32_e32 v32, s26, v32
	v_cmp_lt_i32_e64 s[0:1], s7, v32
	s_or_b64 s[4:5], s[0:1], s[4:5]
	s_waitcnt vmcnt(7)
	v_mul_f32_e32 v90, v43, v43
	s_waitcnt vmcnt(6)
	v_mul_f32_e32 v91, v47, v47
	s_waitcnt vmcnt(5)
	v_mul_f32_e32 v92, v51, v51
	v_fmac_f32_e32 v90, v42, v42
	s_waitcnt vmcnt(3)
	v_mov_b32_e32 v76, v59
	s_waitcnt vmcnt(2)
	v_mov_b32_e32 v77, v63
	v_fmac_f32_e32 v91, v46, v46
	v_mul_f32_e32 v93, v55, v55
	v_mov_b32_e32 v74, v58
	v_mov_b32_e32 v75, v62
	v_fmac_f32_e32 v92, v50, v50
	v_pk_mul_f32 v[76:77], v[76:77], v[76:77]
	v_fmac_f32_e32 v90, v44, v44
	v_fmac_f32_e32 v91, v48, v48
	v_mov_b32_e32 v78, v60
	v_mov_b32_e32 v79, v64
	v_fmac_f32_e32 v93, v54, v54
	v_fmac_f32_e32 v92, v52, v52
	v_pk_fma_f32 v[74:75], v[74:75], v[74:75], v[76:77]
	v_fmac_f32_e32 v90, v45, v45
	v_fmac_f32_e32 v91, v49, v49
	s_waitcnt vmcnt(1)
	v_mov_b32_e32 v84, v67
	s_waitcnt vmcnt(0)
	v_mov_b32_e32 v85, v71
	v_fmac_f32_e32 v93, v56, v56
	v_fmac_f32_e32 v92, v53, v53
	v_pk_fma_f32 v[74:75], v[78:79], v[78:79], v[74:75]
	v_add_f32_e32 v78, v90, v91
	v_mov_b32_e32 v80, v61
	v_mov_b32_e32 v81, v65
	v_mov_b32_e32 v82, v66
	v_mov_b32_e32 v83, v70
	v_pk_mul_f32 v[84:85], v[84:85], v[84:85]
	v_fmac_f32_e32 v93, v57, v57
	v_add_f32_e32 v78, v78, v92
	v_mov_b32_e32 v86, v68
	v_mov_b32_e32 v87, v72
	v_pk_fma_f32 v[76:77], v[82:83], v[82:83], v[84:85]
	v_pk_fma_f32 v[74:75], v[80:81], v[80:81], v[74:75]
	v_add_f32_e32 v78, v78, v93
	v_mov_b32_e32 v88, v69
	v_mov_b32_e32 v89, v73
	v_pk_fma_f32 v[76:77], v[86:87], v[86:87], v[76:77]
	v_add_f32_e32 v74, v78, v74
	v_pk_fma_f32 v[76:77], v[88:89], v[88:89], v[76:77]
	v_add_f32_e32 v74, v74, v75
	v_add_f32_e32 v74, v74, v76
	v_add_f32_e32 v74, v74, v77
	ds_bpermute_b32 v75, v36, v74
	s_waitcnt lgkmcnt(0)
	v_add_f32_e32 v74, v74, v75
	ds_bpermute_b32 v75, v37, v74
	s_waitcnt lgkmcnt(0)
	v_add_f32_e32 v74, v74, v75
	ds_bpermute_b32 v75, v38, v74
	s_waitcnt lgkmcnt(0)
	v_add_f32_e32 v74, v74, v75
	ds_bpermute_b32 v75, v39, v74
	s_waitcnt lgkmcnt(0)
	v_add_f32_e32 v74, v74, v75
	ds_bpermute_b32 v75, v40, v74
	s_waitcnt lgkmcnt(0)
	v_add_f32_e32 v74, v74, v75
	ds_bpermute_b32 v75, v41, v74
	s_waitcnt lgkmcnt(0)
	v_add_f32_e32 v74, v74, v75
	v_fmamk_f32 v74, v74, 0x3a000000, v33
	v_mul_f32_e32 v75, 0x4b800000, v74
	v_cmp_gt_f32_e32 vcc, s6, v74
	s_nop 1
	v_cndmask_b32_e32 v74, v74, v75, vcc
	v_rsq_f32_e32 v74, v74
	s_nop 0
	v_mul_f32_e32 v75, 0x45800000, v74
	v_cndmask_b32_e32 v74, v74, v75, vcc
	v_pk_mul_f32 v[42:43], v[42:43], v[74:75] op_sel_hi:[1,0]
	v_pk_mul_f32 v[44:45], v[44:45], v[74:75] op_sel_hi:[1,0]
	v_pk_mul_f32 v[46:47], v[46:47], v[74:75] op_sel_hi:[1,0]
	v_pk_mul_f32 v[48:49], v[48:49], v[74:75] op_sel_hi:[1,0]
	v_pk_mul_f32 v[50:51], v[50:51], v[74:75] op_sel_hi:[1,0]
	v_pk_mul_f32 v[52:53], v[52:53], v[74:75] op_sel_hi:[1,0]
	v_pk_mul_f32 v[54:55], v[54:55], v[74:75] op_sel_hi:[1,0]
	v_pk_mul_f32 v[56:57], v[56:57], v[74:75] op_sel_hi:[1,0]
	v_pk_mul_f32 v[58:59], v[58:59], v[74:75] op_sel_hi:[1,0]
	v_pk_mul_f32 v[60:61], v[60:61], v[74:75] op_sel_hi:[1,0]
	v_pk_mul_f32 v[62:63], v[62:63], v[74:75] op_sel_hi:[1,0]
	v_pk_mul_f32 v[64:65], v[64:65], v[74:75] op_sel_hi:[1,0]
	v_pk_mul_f32 v[66:67], v[66:67], v[74:75] op_sel_hi:[1,0]
	v_pk_mul_f32 v[68:69], v[68:69], v[74:75] op_sel_hi:[1,0]
	v_pk_mul_f32 v[70:71], v[70:71], v[74:75] op_sel_hi:[1,0]
	v_pk_mul_f32 v[72:73], v[72:73], v[74:75] op_sel_hi:[1,0]
	v_pk_mul_f32 v[44:45], v[2:3], v[44:45]
	v_pk_mul_f32 v[42:43], v[0:1], v[42:43]
	v_pk_mul_f32 v[48:49], v[6:7], v[48:49]
	v_pk_mul_f32 v[46:47], v[4:5], v[46:47]
	v_pk_mul_f32 v[52:53], v[10:11], v[52:53]
	v_pk_mul_f32 v[50:51], v[8:9], v[50:51]
	v_pk_mul_f32 v[56:57], v[14:15], v[56:57]
	v_pk_mul_f32 v[54:55], v[12:13], v[54:55]
	v_pk_mul_f32 v[60:61], v[18:19], v[60:61]
	v_pk_mul_f32 v[58:59], v[16:17], v[58:59]
	v_pk_mul_f32 v[64:65], v[22:23], v[64:65]
	v_pk_mul_f32 v[62:63], v[20:21], v[62:63]
	v_pk_mul_f32 v[68:69], v[26:27], v[68:69]
	v_pk_mul_f32 v[66:67], v[24:25], v[66:67]
	v_pk_mul_f32 v[72:73], v[30:31], v[72:73]
	v_pk_mul_f32 v[70:71], v[28:29], v[70:71]
	global_store_dwordx4 v[34:35], v[42:45], off offset:-4096 nt
	global_store_dwordx4 v[34:35], v[46:49], off offset:-3072 nt
	global_store_dwordx4 v[34:35], v[50:53], off offset:-2048 nt
	global_store_dwordx4 v[34:35], v[54:57], off offset:-1024 nt
	global_store_dwordx4 v[34:35], v[58:61], off nt
	global_store_dwordx4 v[34:35], v[62:65], off offset:1024 nt
	global_store_dwordx4 v[34:35], v[66:69], off offset:2048 nt
	global_store_dwordx4 v[34:35], v[70:73], off offset:3072 nt
	v_lshl_add_u64 v[34:35], v[34:35], 0, s[2:3]
	s_andn2_b64 exec, exec, s[4:5]
	s_cbranch_execnz .LBB0_1709
